# S5 helper: scan output written as one bf16-pair dword per step (XB interleaved re/im, CM re-laid once per head): 16 fewer LDS writes per chunk
# speedup vs baseline: 1.0084x; 1.0070x over previous
.LBB0_391:
	s_andn2_b64 vcc, exec, s[36:37]
	s_cbranch_vccnz .LBB0_411
	s_cmp_lg_u32 s2, 0
	s_cbranch_scc1 .Lcm_done
	v_and_b32_e32 v216, 48, v98
	v_add_u32_e32 v217, v145, v216
	v_lshl_add_u32 v218, v216, 1, v217
	ds_read_b128 v[220:223], v217 offset:16640
	ds_read_b128 v[224:227], v217 offset:16656
	ds_read_b128 v[228:231], v217 offset:16768
	ds_read_b128 v[244:247], v217 offset:16784
	s_mov_b32 s8, 0xffff0000
	s_waitcnt lgkmcnt(0)
	v_and_b32_e32 v219, 0xffff, v220
	v_lshl_or_b32 v248, v228, 16, v219
	v_lshrrev_b32_e32 v219, 16, v220
	v_and_or_b32 v249, v228, s8, v219
	v_and_b32_e32 v219, 0xffff, v221
	v_lshl_or_b32 v250, v229, 16, v219
	v_lshrrev_b32_e32 v219, 16, v221
	v_and_or_b32 v251, v229, s8, v219
	ds_write_b128 v218, v[248:251] offset:16640
	v_and_b32_e32 v219, 0xffff, v222
	v_lshl_or_b32 v92, v230, 16, v219
	v_lshrrev_b32_e32 v219, 16, v222
	v_and_or_b32 v93, v230, s8, v219
	v_and_b32_e32 v219, 0xffff, v223
	v_lshl_or_b32 v94, v231, 16, v219
	v_lshrrev_b32_e32 v219, 16, v223
	v_and_or_b32 v95, v231, s8, v219
	ds_write_b128 v218, v[92:95] offset:16656
	v_and_b32_e32 v219, 0xffff, v224
	v_lshl_or_b32 v248, v244, 16, v219
	v_lshrrev_b32_e32 v219, 16, v224
	v_and_or_b32 v249, v244, s8, v219
	v_and_b32_e32 v219, 0xffff, v225
	v_lshl_or_b32 v250, v245, 16, v219
	v_lshrrev_b32_e32 v219, 16, v225
	v_and_or_b32 v251, v245, s8, v219
	ds_write_b128 v218, v[248:251] offset:16672
	v_and_b32_e32 v219, 0xffff, v226
	v_lshl_or_b32 v92, v246, 16, v219
	v_lshrrev_b32_e32 v219, 16, v226
	v_and_or_b32 v93, v246, s8, v219
	v_and_b32_e32 v219, 0xffff, v227
	v_lshl_or_b32 v94, v247, 16, v219
	v_lshrrev_b32_e32 v219, 16, v227
	v_and_or_b32 v95, v247, s8, v219
	ds_write_b128 v218, v[92:95] offset:16688
	s_waitcnt lgkmcnt(0)
.Lcm_done:
	s_add_i32 s3, s2, 1
	s_cmpk_eq_i32 s2, 0x7f
	s_cselect_b64 s[38:39], -1, 0
	s_cmpk_lg_i32 s2, 0x7f
	s_cselect_b64 s[50:51], -1, 0
	s_and_b64 vcc, exec, s[38:39]
	s_cbranch_vccnz .LBB0_394
	s_lshl_b32 s8, s3, 4
	s_or_b32 s26, s8, s96
	s_add_u32 s8, s30, s26
	s_addc_u32 s9, s31, 0
	s_mul_i32 s27, s9, 0xe00
	v_mad_u64_u32 v[2:3], s[24:25], s8, v240, v[70:71]
	s_lshl_b64 s[8:9], s[8:9], 9
	v_lshl_add_u64 v[8:9], s[8:9], 0, v[24:25]
	s_or_b32 s8, s26, 4
	s_add_u32 s8, s30, s8
	s_addc_u32 s9, s31, 0
	v_add_u32_e32 v3, s27, v3
	s_mul_i32 s27, s9, 0xe00
	v_mad_u64_u32 v[16:17], s[24:25], s8, v240, v[70:71]
	v_add_u32_e32 v17, s27, v17
	s_lshl_b64 s[8:9], s[8:9], 9
	global_load_ushort v176, v[16:17], off
	global_load_ushort v177, v[16:17], off offset:-3584
	global_load_ushort v178, v[16:17], off offset:-2560
	global_load_ushort v179, v[16:17], off offset:-1536
	global_load_ushort v180, v[2:3], off
	global_load_ushort v181, v[16:17], off offset:1024
	global_load_ushort v182, v[2:3], off offset:1024
	global_load_ushort v183, v[16:17], off offset:2048
	global_load_ushort v184, v[2:3], off offset:2048
	global_load_ushort v185, v[2:3], off offset:-3584
	global_load_ushort v186, v[2:3], off offset:-2560
	global_load_ushort v187, v[2:3], off offset:-1536
	v_lshl_add_u64 v[2:3], s[8:9], 0, v[24:25]
	s_or_b32 s8, s26, 8
	s_add_u32 s36, s30, s8
	s_addc_u32 s37, s31, 0
	s_lshl_b64 s[8:9], s[36:37], 9
	v_lshl_add_u64 v[26:27], s[8:9], 0, v[24:25]
	s_or_b32 s8, s26, 12
	s_add_u32 s52, s30, s8
	s_addc_u32 s53, s31, 0
	s_lshl_b64 s[8:9], s[52:53], 9
	v_lshlrev_b64 v[8:9], 1, v[8:9]
	v_lshlrev_b64 v[2:3], 1, v[2:3]
	v_lshl_add_u64 v[30:31], s[8:9], 0, v[24:25]
	v_lshl_add_u64 v[10:11], s[20:21], 0, v[8:9]
	v_lshl_add_u64 v[16:17], s[20:21], 0, v[2:3]
	v_lshl_add_u64 v[2:3], s[22:23], 0, v[2:3]
	v_lshlrev_b64 v[26:27], 1, v[26:27]
	v_lshlrev_b64 v[30:31], 1, v[30:31]
	v_lshl_add_u64 v[8:9], s[22:23], 0, v[8:9]
	v_lshl_add_u64 v[28:29], s[20:21], 0, v[26:27]
	v_lshl_add_u64 v[26:27], s[22:23], 0, v[26:27]
	v_lshl_add_u64 v[32:33], s[20:21], 0, v[30:31]
	v_lshl_add_u64 v[30:31], s[22:23], 0, v[30:31]
	global_load_ushort v188, v[16:17], off
	s_nop 0
	global_load_ushort v189, v[10:11], off
	s_nop 0
	global_load_ushort v190, v[2:3], off
	global_load_ushort v191, v[28:29], off
	global_load_ushort v192, v[26:27], off
	global_load_ushort v193, v[32:33], off
	global_load_ushort v194, v[30:31], off
	global_load_ushort v195, v[8:9], off
	s_mul_i32 s24, s37, 0xe00
	v_mad_u64_u32 v[2:3], s[8:9], s36, v240, v[70:71]
	v_add_u32_e32 v3, s24, v3
	s_mul_i32 s24, s53, 0xe00
	v_mad_u64_u32 v[8:9], s[8:9], s52, v240, v[70:71]
	v_add_u32_e32 v9, s24, v9
	global_load_ushort v196, v[2:3], off
	global_load_ushort v197, v[8:9], off
	global_load_ushort v198, v[2:3], off offset:1024
	global_load_ushort v199, v[8:9], off offset:1024
	global_load_ushort v200, v[2:3], off offset:2048
	global_load_ushort v201, v[8:9], off offset:2048
	global_load_ushort v202, v[2:3], off offset:-3584
	global_load_ushort v203, v[8:9], off offset:-3584
	global_load_ushort v204, v[2:3], off offset:-2560
	global_load_ushort v205, v[8:9], off offset:-2560
	s_nop 0
	global_load_ushort v206, v[2:3], off offset:-1536
	s_nop 0
	global_load_ushort v207, v[8:9], off offset:-1536

.LBB0_398:
	s_or_b64 exec, exec, s[38:39]
	v_lshl_or_b32 v2, s8, 10, v142
	v_mov_b32_e32 v3, v0
	v_lshl_add_u64 v[2:3], v[68:69], 0, v[2:3]
	global_load_ushort v212, v[2:3], off
	global_load_ushort v213, v[2:3], off offset:1024
	global_load_ushort v214, v[2:3], off offset:2048
	global_load_ushort v215, v[2:3], off offset:3072
	v_add_u32_e32 v91, v143, v102
	ds_read_b128 v[92:95], v91 offset:12544
	ds_read_b128 v[164:167], v91 offset:13056
	ds_read_b128 v[216:219], v91 offset:13568
	ds_read_b128 v[220:223], v146 offset:12544
	ds_read_b128 v[224:227], v91 offset:14592
	ds_read_b128 v[228:231], v91 offset:15104
	ds_read_b128 v[244:247], v91 offset:15616
	ds_read_b128 v[248:251], v147 offset:12544
	v_add_u32_e32 v96, 0xf000, v138
	v_add_u32_e32 v97, 0xf400, v138
	v_add_u32_e32 v159, 0xf800, v138
	s_andn2_b64 vcc, exec, s[50:51]
	s_waitcnt lgkmcnt(7)
	v_mfma_f32_16x16x32_bf16 v[92:95], v[12:15], v[92:95], 0
	s_waitcnt lgkmcnt(6)
	v_mfma_f32_16x16x32_bf16 v[164:167], v[12:15], v[164:167], 0
	s_waitcnt lgkmcnt(5)
	v_mfma_f32_16x16x32_bf16 v[216:219], v[12:15], v[216:219], 0
	s_waitcnt lgkmcnt(4)
	v_mfma_f32_16x16x32_bf16 v[220:223], v[12:15], v[220:223], 0
	s_waitcnt lgkmcnt(3)
	v_mfma_f32_16x16x32_bf16 v[224:227], v[12:15], v[224:227], 0
	s_waitcnt lgkmcnt(2)
	v_mfma_f32_16x16x32_bf16 v[228:231], v[12:15], v[228:231], 0
	s_waitcnt lgkmcnt(1)
	v_mfma_f32_16x16x32_bf16 v[244:247], v[12:15], v[244:247], 0
	s_waitcnt lgkmcnt(0)
	v_mfma_f32_16x16x32_bf16 v[248:251], v[12:15], v[248:251], 0
	ds_write2_b32 v96, v92, v164 offset0:192 offset1:208
	ds_write2_b32 v97, v93, v165 offset0:64 offset1:80
	ds_write2_b32 v97, v94, v166 offset0:192 offset1:208
	ds_write2_b32 v159, v95, v167 offset0:64 offset1:80
	ds_write2_b32 v96, v216, v220 offset0:224 offset1:240
	ds_write2_b32 v97, v217, v221 offset0:96 offset1:112
	ds_write2_b32 v97, v218, v222 offset0:224 offset1:240
	ds_write2_b32 v159, v219, v223 offset0:96 offset1:112
	ds_write2_b32 v97, v224, v228 offset1:16
	ds_write2_b32 v97, v225, v229 offset0:128 offset1:144
	ds_write2_b32 v159, v226, v230 offset1:16
	ds_write2_b32 v159, v227, v231 offset0:128 offset1:144
	ds_write2_b32 v97, v244, v248 offset0:32 offset1:48
	ds_write2_b32 v97, v245, v249 offset0:160 offset1:176
	ds_write2_b32 v159, v246, v250 offset0:32 offset1:48
	ds_write2_b32 v159, v247, v251 offset0:160 offset1:176
	s_waitcnt lgkmcnt(0)
	v_lshl_add_u32 v91, v98, 1, v141
	ds_read2st64_b32 v[216:217], v140 offset1:1
	ds_read2st64_b32 v[218:219], v140 offset0:2 offset1:3
	ds_read2st64_b32 v[220:221], v140 offset0:4 offset1:5
	ds_read2st64_b32 v[222:223], v140 offset0:6 offset1:7
	ds_read2st64_b32 v[224:225], v140 offset0:8 offset1:9
	ds_read2st64_b32 v[226:227], v140 offset0:10 offset1:11
	ds_read2st64_b32 v[228:229], v140 offset0:12 offset1:13
	ds_read2st64_b32 v[230:231], v140 offset0:14 offset1:15
	ds_read2st64_b32 v[244:245], v140 offset0:16 offset1:17
	ds_read2st64_b32 v[246:247], v140 offset0:18 offset1:19
	ds_read2st64_b32 v[248:249], v140 offset0:20 offset1:21
	ds_read2st64_b32 v[250:251], v140 offset0:22 offset1:23
	ds_read2st64_b32 v[92:93], v140 offset0:24 offset1:25
	ds_read2st64_b32 v[94:95], v140 offset0:26 offset1:27
	ds_read2st64_b32 v[164:165], v140 offset0:28 offset1:29
	ds_read2st64_b32 v[166:167], v140 offset0:30 offset1:31
	s_waitcnt lgkmcnt(15)
	v_pk_fma_f32 v[14:15], v[64:65], v[60:61], v[216:217] op_sel:[0,1,0] op_sel_hi:[0,0,1] neg_lo:[1,0,0]
	v_pk_fma_f32 v[60:61], v[56:57], v[60:61], v[14:15] op_sel_hi:[0,1,1]
	v_cvt_pk_bf16_f32 v12, v60, v61
	ds_write_b32 v91, v12 offset:8192
	s_waitcnt lgkmcnt(15)
	v_pk_fma_f32 v[14:15], v[64:65], v[60:61], v[218:219] op_sel:[0,1,0] op_sel_hi:[0,0,1] neg_lo:[1,0,0]
	v_pk_fma_f32 v[60:61], v[56:57], v[60:61], v[14:15] op_sel_hi:[0,1,1]
	v_cvt_pk_bf16_f32 v13, v60, v61
	ds_write_b32 v91, v13 offset:8464
	s_waitcnt lgkmcnt(15)
	v_pk_fma_f32 v[14:15], v[64:65], v[60:61], v[220:221] op_sel:[0,1,0] op_sel_hi:[0,0,1] neg_lo:[1,0,0]
	v_pk_fma_f32 v[60:61], v[56:57], v[60:61], v[14:15] op_sel_hi:[0,1,1]
	v_cvt_pk_bf16_f32 v12, v60, v61
	ds_write_b32 v91, v12 offset:8736
	s_waitcnt lgkmcnt(15)
	v_pk_fma_f32 v[14:15], v[64:65], v[60:61], v[222:223] op_sel:[0,1,0] op_sel_hi:[0,0,1] neg_lo:[1,0,0]
	v_pk_fma_f32 v[60:61], v[56:57], v[60:61], v[14:15] op_sel_hi:[0,1,1]
	v_cvt_pk_bf16_f32 v13, v60, v61
	ds_write_b32 v91, v13 offset:9008
	s_waitcnt lgkmcnt(15)
	v_pk_fma_f32 v[14:15], v[64:65], v[60:61], v[224:225] op_sel:[0,1,0] op_sel_hi:[0,0,1] neg_lo:[1,0,0]
	v_pk_fma_f32 v[60:61], v[56:57], v[60:61], v[14:15] op_sel_hi:[0,1,1]
	v_cvt_pk_bf16_f32 v12, v60, v61
	ds_write_b32 v91, v12 offset:9280
	s_waitcnt lgkmcnt(15)
	v_pk_fma_f32 v[14:15], v[64:65], v[60:61], v[226:227] op_sel:[0,1,0] op_sel_hi:[0,0,1] neg_lo:[1,0,0]
	v_pk_fma_f32 v[60:61], v[56:57], v[60:61], v[14:15] op_sel_hi:[0,1,1]
	v_cvt_pk_bf16_f32 v13, v60, v61
	ds_write_b32 v91, v13 offset:9552
	s_waitcnt lgkmcnt(15)
	v_pk_fma_f32 v[14:15], v[64:65], v[60:61], v[228:229] op_sel:[0,1,0] op_sel_hi:[0,0,1] neg_lo:[1,0,0]
	v_pk_fma_f32 v[60:61], v[56:57], v[60:61], v[14:15] op_sel_hi:[0,1,1]
	v_cvt_pk_bf16_f32 v12, v60, v61
	ds_write_b32 v91, v12 offset:9824
	s_waitcnt lgkmcnt(15)
	v_pk_fma_f32 v[14:15], v[64:65], v[60:61], v[230:231] op_sel:[0,1,0] op_sel_hi:[0,0,1] neg_lo:[1,0,0]
	v_pk_fma_f32 v[60:61], v[56:57], v[60:61], v[14:15] op_sel_hi:[0,1,1]
	v_cvt_pk_bf16_f32 v13, v60, v61
	ds_write_b32 v91, v13 offset:10096
	s_waitcnt lgkmcnt(15)
	v_pk_fma_f32 v[14:15], v[64:65], v[60:61], v[244:245] op_sel:[0,1,0] op_sel_hi:[0,0,1] neg_lo:[1,0,0]
	v_pk_fma_f32 v[60:61], v[56:57], v[60:61], v[14:15] op_sel_hi:[0,1,1]
	v_cvt_pk_bf16_f32 v12, v60, v61
	ds_write_b32 v91, v12 offset:10368
	s_waitcnt lgkmcnt(15)
	v_pk_fma_f32 v[14:15], v[64:65], v[60:61], v[246:247] op_sel:[0,1,0] op_sel_hi:[0,0,1] neg_lo:[1,0,0]
	v_pk_fma_f32 v[60:61], v[56:57], v[60:61], v[14:15] op_sel_hi:[0,1,1]
	v_cvt_pk_bf16_f32 v13, v60, v61
	ds_write_b32 v91, v13 offset:10640
	s_waitcnt lgkmcnt(15)
	v_pk_fma_f32 v[14:15], v[64:65], v[60:61], v[248:249] op_sel:[0,1,0] op_sel_hi:[0,0,1] neg_lo:[1,0,0]
	v_pk_fma_f32 v[60:61], v[56:57], v[60:61], v[14:15] op_sel_hi:[0,1,1]
	v_cvt_pk_bf16_f32 v12, v60, v61
	ds_write_b32 v91, v12 offset:10912
	s_waitcnt lgkmcnt(15)
	v_pk_fma_f32 v[14:15], v[64:65], v[60:61], v[250:251] op_sel:[0,1,0] op_sel_hi:[0,0,1] neg_lo:[1,0,0]
	v_pk_fma_f32 v[60:61], v[56:57], v[60:61], v[14:15] op_sel_hi:[0,1,1]
	v_cvt_pk_bf16_f32 v13, v60, v61
	ds_write_b32 v91, v13 offset:11184
	s_waitcnt lgkmcnt(15)
	v_pk_fma_f32 v[14:15], v[64:65], v[60:61], v[92:93] op_sel:[0,1,0] op_sel_hi:[0,0,1] neg_lo:[1,0,0]
	v_pk_fma_f32 v[60:61], v[56:57], v[60:61], v[14:15] op_sel_hi:[0,1,1]
	v_cvt_pk_bf16_f32 v12, v60, v61
	ds_write_b32 v91, v12 offset:11456
	s_waitcnt lgkmcnt(15)
	v_pk_fma_f32 v[14:15], v[64:65], v[60:61], v[94:95] op_sel:[0,1,0] op_sel_hi:[0,0,1] neg_lo:[1,0,0]
	v_pk_fma_f32 v[60:61], v[56:57], v[60:61], v[14:15] op_sel_hi:[0,1,1]
	v_cvt_pk_bf16_f32 v13, v60, v61
	ds_write_b32 v91, v13 offset:11728
	s_waitcnt lgkmcnt(15)
	v_pk_fma_f32 v[14:15], v[64:65], v[60:61], v[164:165] op_sel:[0,1,0] op_sel_hi:[0,0,1] neg_lo:[1,0,0]
	v_pk_fma_f32 v[60:61], v[56:57], v[60:61], v[14:15] op_sel_hi:[0,1,1]
	v_cvt_pk_bf16_f32 v12, v60, v61
	ds_write_b32 v91, v12 offset:12000
	s_waitcnt lgkmcnt(15)
	v_pk_fma_f32 v[14:15], v[64:65], v[60:61], v[166:167] op_sel:[0,1,0] op_sel_hi:[0,0,1] neg_lo:[1,0,0]
	v_pk_fma_f32 v[60:61], v[56:57], v[60:61], v[14:15] op_sel_hi:[0,1,1]
	v_cvt_pk_bf16_f32 v13, v60, v61
	ds_write_b32 v91, v13 offset:12272
	s_waitcnt lgkmcnt(0)
	ds_read_b128 v[12:15], v144 offset:8192
	ds_read_b128 v[92:95], v145 offset:16640
	ds_read_b128 v[216:219], v144 offset:8256
	ds_read_b128 v[220:223], v145 offset:16704
	ds_read_b128 v[224:227], v144 offset:8320
	ds_read_b128 v[228:231], v145 offset:16768
	ds_read_b128 v[244:247], v144 offset:8384
	ds_read_b128 v[248:251], v145 offset:16832
	s_waitcnt lgkmcnt(6)
	v_mfma_f32_16x16x32_bf16 v[12:15], v[12:15], v[92:95], 0
	s_waitcnt lgkmcnt(4)
	v_mfma_f32_16x16x32_bf16 v[12:15], v[216:219], v[220:223], v[12:15]
	s_waitcnt lgkmcnt(2)
	v_mfma_f32_16x16x32_bf16 v[12:15], v[224:227], v[228:231], v[12:15]
	s_waitcnt lgkmcnt(0)
	v_mfma_f32_16x16x32_bf16 v[12:15], v[244:247], v[248:251], v[12:15]
	s_nop 7
	s_waitcnt vmcnt(0)
	v_lshlrev_b32_e32 v88, 16, v212
	v_lshlrev_b32_e32 v89, 16, v213
	v_lshlrev_b32_e32 v90, 16, v214
	v_lshlrev_b32_e32 v91, 16, v215
	v_pk_fma_f32 v[12:13], v[148:149], v[88:89], v[12:13] op_sel_hi:[0,1,1]
	v_pk_fma_f32 v[14:15], v[148:149], v[90:91], v[14:15] op_sel_hi:[0,1,1]
	v_mov_b32_e32 v88, 0x3dd2d3e8
	v_mov_b32_e32 v90, 0x40135761
	v_pk_mul_f32 v[92:93], v[12:13], v[12:13]
	v_pk_mul_f32 v[94:95], v[14:15], v[14:15]
	v_pk_fma_f32 v[92:93], v[92:93], v[88:89], v[90:91] op_sel_hi:[1,0,0]
	v_pk_fma_f32 v[94:95], v[94:95], v[88:89], v[90:91] op_sel_hi:[1,0,0]
	v_pk_mul_f32 v[92:93], v[92:93], v[12:13]
	v_pk_mul_f32 v[94:95], v[94:95], v[14:15]
	v_mov_b32_e32 v88, 1.0
	v_exp_f32_e32 v92, v92
	v_exp_f32_e32 v93, v93
	v_exp_f32_e32 v94, v94
	v_exp_f32_e32 v95, v95
	s_nop 0
	v_pk_add_f32 v[92:93], v[92:93], v[88:89] op_sel_hi:[1,0]
	v_pk_add_f32 v[94:95], v[94:95], v[88:89] op_sel_hi:[1,0]
	v_rcp_f32_e32 v92, v92
	v_rcp_f32_e32 v93, v93
	v_rcp_f32_e32 v94, v94
	v_rcp_f32_e32 v95, v95
	s_nop 0
	v_pk_fma_f32 v[12:13], v[12:13], v[92:93], v[12:13] neg_lo:[1,0,0] neg_hi:[1,0,0]
	v_pk_fma_f32 v[14:15], v[14:15], v[94:95], v[14:15] neg_lo:[1,0,0] neg_hi:[1,0,0]
	v_cvt_pk_bf16_f32 v12, v12, v13
	v_cvt_pk_bf16_f32 v14, v14, v15
	global_store_short v[2:3], v12, off
	global_store_short_d16_hi v[2:3], v12, off offset:1024
	global_store_short v[2:3], v14, off offset:2048
	global_store_short_d16_hi v[2:3], v14, off offset:3072
	s_waitcnt lgkmcnt(0)
	v_lshlrev_b32_e32 v1, 2, v128
	s_cbranch_vccnz .LBB0_408
	s_waitcnt vmcnt(4)
	v_lshlrev_b32_e32 v16, 16, v176
	v_lshlrev_b32_e32 v30, 16, v177
	v_lshlrev_b32_e32 v32, 16, v178
	v_lshlrev_b32_e32 v36, 16, v179
	v_lshlrev_b32_e32 v17, 16, v180
	v_lshlrev_b32_e32 v26, 16, v181
	v_lshlrev_b32_e32 v27, 16, v182
	v_lshlrev_b32_e32 v28, 16, v183
	v_lshlrev_b32_e32 v29, 16, v184
	v_lshlrev_b32_e32 v31, 16, v185
	v_lshlrev_b32_e32 v33, 16, v186
	v_lshlrev_b32_e32 v37, 16, v187
	v_lshlrev_b32_e32 v34, 16, v188
	v_lshlrev_b32_e32 v35, 16, v189
	v_lshlrev_b32_e32 v38, 16, v190
	v_lshlrev_b32_e32 v39, 16, v195
	v_lshlrev_b32_e32 v40, 16, v197
	v_lshlrev_b32_e32 v43, 16, v198
	v_lshlrev_b32_e32 v42, 16, v199
	v_lshlrev_b32_e32 v45, 16, v200
	v_lshlrev_b32_e32 v44, 16, v201
	v_lshlrev_b32_e32 v46, 16, v203
	v_lshlrev_b32_e32 v49, 16, v204
	v_lshlrev_b32_e32 v48, 16, v205
	v_lshlrev_b32_e32 v41, 16, v196
	v_lshlrev_b32_e32 v47, 16, v202
	v_lshlrev_b32_e32 v51, 16, v206
	v_lshlrev_b32_e32 v50, 16, v207
	v_lshlrev_b32_e32 v53, 16, v191
	v_lshlrev_b32_e32 v52, 16, v193
	v_lshlrev_b32_e32 v55, 16, v192
	v_lshlrev_b32_e32 v54, 16, v194
	v_add_f32_e32 v88, v155, v35
	v_mul_f32_e32 v88, 0xbfb8aa3b, v88
	v_exp_f32_e32 v88, v88
	v_pk_add_f32 v[12:13], v[32:33], v[26:27] neg_lo:[0,1] neg_hi:[0,1]
	v_pk_add_f32 v[2:3], v[30:31], v[16:17] neg_lo:[0,1] neg_hi:[0,1]
	v_fma_f32 v13, v150, v13, v27
	v_add_f32_e32 v88, 1.0, v88
	v_rcp_f32_e32 v88, v88
	v_mul_f32_e32 v92, v157, v13
	v_fma_f32 v3, v149, v3, v17
	s_bitcmp1_b32 s3, 0
	v_mul_f32_e32 v89, 0xbf6002b1, v88
	v_cmp_gt_f32_e32 vcc, s85, v89
	s_cselect_b32 s8, 0x5000, 0
	v_mov_b32_e32 v94, v0
	v_cndmask_b32_e32 v89, 0, v239, vcc
	v_fmac_f32_e32 v89, 0xbf6002b1, v88
	v_exp_f32_e32 v88, v89
	v_cndmask_b32_e32 v89, 0, v236, vcc
	s_add_i32 s9, s8, 0
	s_mul_i32 s8, s3, 0xab
	v_ldexp_f32 v90, v88, v89
	v_add_f32_e32 v88, v154, v39
	v_mul_f32_e32 v88, 0xbfb8aa3b, v88
	v_exp_f32_e32 v88, v88
	v_mov_b32_e32 v89, v0
	s_bfe_u32 s8, s8, 0x70009
	s_mul_i32 s8, s8, 3
	v_add_f32_e32 v88, 1.0, v88
	v_rcp_f32_e32 v91, v88
	v_mul_f32_e32 v88, v92, v92
	s_sub_i32 s8, s3, s8
	s_and_b32 s8, s8, 0xff
	v_mov_b32_dpp v89, v88 quad_perm:[1,0,3,2] row_mask:0xf bank_mask:0xf
	v_fmac_f32_e32 v89, v92, v92
	s_mulk_i32 s8, 0x1100
	s_add_i32 s8, s8, 0
	v_add_f32_dpp v88, v89, v89 quad_perm:[2,3,0,1] row_mask:0xf bank_mask:0xf bound_ctrl:1
	v_pk_add_f32 v[14:15], v[36:37], v[28:29] neg_lo:[0,1] neg_hi:[0,1]
	s_nop 0
	v_add_f32_dpp v88, v88, v88 row_half_mirror row_mask:0xf bank_mask:0xf bound_ctrl:1
	v_fma_f32 v15, v151, v15, v29
	s_nop 0
	v_add_f32_dpp v88, v88, v88 row_mirror row_mask:0xf bank_mask:0xf bound_ctrl:1
	s_nop 0
	s_nop 1
	v_add_f32_dpp v88, v88, v88 row_bcast:15 row_mask:0xa bank_mask:0xf
	s_nop 1
	v_add_f32_dpp v88, v88, v88 row_bcast:31 row_mask:0xc bank_mask:0xf
	s_nop 0
	v_readlane_b32 s26, v88, 63
	s_nop 1
	v_mov_b32_e32 v88, s26
	v_add_f32_e32 v88, 0x2b8cbccc, v88
	v_cmp_gt_f32_e32 vcc, s82, v88
	v_mul_f32_e32 v89, 0x4b800000, v88
	s_nop 0
	v_cndmask_b32_e32 v88, v88, v89, vcc
	v_rsq_f32_e32 v88, v88
	s_nop 0
	v_mul_f32_e32 v89, 0x45800000, v88
	v_cndmask_b32_e32 v88, v88, v89, vcc
	v_add_f32_e32 v89, -1.0, v91
	v_fma_f32 v89, v158, v89, 1.0
	v_mul_f32_e32 v13, v89, v13
	v_mul_f32_e32 v89, v13, v3
	v_mul_f32_e32 v93, v156, v89
	v_mul_f32_e64 v88, v92, -v88
	s_nop 0
	v_mov_b32_dpp v94, v93 quad_perm:[1,0,3,2] row_mask:0xf bank_mask:0xf
	v_fmac_f32_e32 v94, v156, v89
	s_nop 1
	v_add_f32_dpp v89, v94, v94 quad_perm:[2,3,0,1] row_mask:0xf bank_mask:0xf bound_ctrl:1
	s_nop 1
	v_add_f32_dpp v89, v89, v89 row_half_mirror row_mask:0xf bank_mask:0xf bound_ctrl:1
	s_nop 1
	v_add_f32_dpp v89, v89, v89 row_mirror row_mask:0xf bank_mask:0xf bound_ctrl:1
	s_nop 0
	s_nop 1
	v_add_f32_dpp v89, v89, v89 row_bcast:15 row_mask:0xa bank_mask:0xf
	s_nop 1
	v_add_f32_dpp v89, v89, v89 row_bcast:31 row_mask:0xc bank_mask:0xf
	s_nop 0
	v_readlane_b32 s38, v89, 63
	v_add_u32_e32 v89, s9, v1
	ds_write2st64_b32 v89, v90, v88 offset1:16
	v_mul_f32_e64 v88, v91, -v88
	ds_write2st64_b32 v89, v88, v13 offset0:32 offset1:48
	ds_write_b32 v89, v3 offset:16384
	v_add_u32_e32 v3, s8, v1
	ds_write_b32 v3, v15 offset:40960
	s_and_saveexec_b64 s[50:51], s[44:45]
	s_cbranch_execz .LBB0_401
	s_lshl_b32 s24, s96, 2
	s_add_i32 s24, s8, s24
	v_mov_b32_e32 v13, s24
	v_mov_b32_e32 v3, s38
	ds_write_b32 v13, v3 offset:45056
